# v37 + hyena data step: conv neighbours through DPP wave_shr:1 / wave_shl:1 moves instead of 32 ds_bpermute
# speedup vs baseline: 1.0193x; 1.0004x over previous
; template <bool INV> __device__ __forceinline__ void dft16(f32x2 (&x)[16]) {
; #pragma unroll
;     for (int b = 0; b < 4; ++b) r4<INV>(x[b], x[4 + b], x[8 + b], x[12 + b]);
;     const float sg = INV ? -1.f : 1.f;
;     const f32x2 W1 = {0.92387953251f, -0.38268343236f * sg}, W2 = {0.70710678118f, -0.70710678118f * sg}, W3 = {0.38268343236f, -0.92387953251f * sg},
;                 W4 = {0.f, -1.f * sg}, W6 = {-0.70710678118f, -0.70710678118f * sg}, W9 = {-0.92387953251f, 0.38268343236f * sg};
;     x[5] = cmul(x[5], W1); x[9] = cmul(x[9], W2); x[13] = cmul(x[13], W3);
;     x[6] = cmul(x[6], W2); x[10] = cmul(x[10], W4); x[14] = cmul(x[14], W6);
;     x[7] = cmul(x[7], W3); x[11] = cmul(x[11], W6); x[15] = cmul(x[15], W9);
; #pragma unroll
;     for (int c = 0; c < 4; ++c) r4<INV>(x[4 * c], x[4 * c + 1], x[4 * c + 2], x[4 * c + 3]);
; }
; template <bool INV> __device__ __forceinline__ void bfly16(f32x2 (&x)[16], const LAS f32x2* TH, const LAS f32x2* TL, int tw) {
;     f32x2 W = tw32k(TH, TL, tw); if (INV) W.y = -W.y;
;     if (INV) { f32x2 p = W;
; #pragma unroll
;         for (int q = 1; q < 16; ++q) { x[q] = cmul(x[q], p); if (q < 15) p = cmul(p, W); } }
;     dft16<INV>(x);
;     if (!INV) { f32x2 p = W;
; #pragma unroll
;         for (int r = 1; r < 16; ++r) { x[4 * (r & 3) + (r >> 2)] = cmul(x[4 * (r & 3) + (r >> 2)], p); if (r < 15) p = cmul(p, W); } }
; }
; template <bool INV> __device__ __forceinline__ void bfly16_tab(f32x2 (&x)[16], const LAS f32x2* T, int tstride, int j) {
;     if (INV) {
; #pragma unroll
;         for (int q = 1; q < 16; ++q) { f32x2 p = T[q * tstride + j]; p.y = -p.y; x[q] = cmul(x[q], p); } }
;     dft16<INV>(x);
;     if (!INV) {
; #pragma unroll
;         for (int r = 1; r < 16; ++r) { const f32x2 p = T[r * tstride + j]; x[4 * (r & 3) + (r >> 2)] = cmul(x[4 * (r & 3) + (r >> 2)], p); } }
; }
; template <bool INV> __device__ __forceinline__ void pass16_s4(LAS f32x2* X, const LAS f32x2* TH, const LAS f32x2* TL, int tid) {
; #pragma unroll 1
;     for (int s = 0; s < 2; ++s) {
;         const int b = tid + NTHR * s, blk = b >> 2, jj = b & 3;
;         LAS f32x2* P = X + blk * 68 + jj;
;         f32x2 x[16];
; #pragma unroll
;         for (int q = 0; q < 16; ++q) x[q] = P[4 * q];
;         bfly16_tab<INV>(x, TH - 1024, 4, jj);
; #pragma unroll
;         for (int c = 0; c < 4; ++c)
; #pragma unroll
.LBB0_700:
	v_add_u32_e32 v128, s0, v140
	v_lshrrev_b32_e32 v147, 2, v128
	v_mad_u32_u24 v151, v147, s43, v144
	ds_read_b64 v[0:1], v151 offset:0
	ds_read_b64 v[2:3], v151 offset:256
	ds_read_b64 v[4:5], v151 offset:32
	ds_read_b64 v[6:7], v151 offset:288
	ds_read_b64 v[8:9], v151 offset:64
	ds_read_b64 v[10:11], v151 offset:320
	ds_read_b64 v[12:13], v151 offset:96
	ds_read_b64 v[14:15], v151 offset:352
	ds_read_b64 v[16:17], v151 offset:128
	ds_read_b64 v[18:19], v151 offset:384
	ds_read_b64 v[20:21], v151 offset:160
	ds_read_b64 v[22:23], v151 offset:416
	ds_read_b64 v[24:25], v151 offset:192
	ds_read_b64 v[26:27], v151 offset:448
	ds_read_b64 v[28:29], v151 offset:224
	ds_read_b64 v[30:31], v151 offset:480
	s_cmp_eq_u32 s0, 0
	s_movk_i32 s0, 0x200
	s_mov_b64 s[36:37], 0
	s_waitcnt lgkmcnt(14)
	v_pk_add_f32 v[32:33], v[0:1], v[2:3]
	s_waitcnt lgkmcnt(12)
	v_pk_add_f32 v[34:35], v[4:5], v[6:7]
	s_waitcnt lgkmcnt(10)
	v_pk_add_f32 v[36:37], v[8:9], v[10:11]
	s_waitcnt lgkmcnt(8)
	v_pk_add_f32 v[38:39], v[12:13], v[14:15]
	v_pk_add_f32 v[0:1], v[0:1], v[2:3] neg_lo:[0,1] neg_hi:[0,1]
	v_pk_add_f32 v[6:7], v[4:5], v[6:7] neg_lo:[0,1] neg_hi:[0,1]
	v_pk_add_f32 v[8:9], v[8:9], v[10:11] neg_lo:[0,1] neg_hi:[0,1]
	v_pk_add_f32 v[12:13], v[12:13], v[14:15] neg_lo:[0,1] neg_hi:[0,1]
	s_waitcnt lgkmcnt(6)
	v_pk_add_f32 v[14:15], v[16:17], v[18:19]
	s_waitcnt lgkmcnt(4)
	v_pk_add_f32 v[10:11], v[20:21], v[22:23]
	s_waitcnt lgkmcnt(2)
	v_pk_add_f32 v[4:5], v[24:25], v[26:27]
	s_waitcnt lgkmcnt(0)
	v_pk_add_f32 v[2:3], v[28:29], v[30:31]
	v_pk_add_f32 v[18:19], v[16:17], v[18:19] neg_lo:[0,1] neg_hi:[0,1]
	v_pk_add_f32 v[22:23], v[20:21], v[22:23] neg_lo:[0,1] neg_hi:[0,1]
	v_pk_add_f32 v[26:27], v[24:25], v[26:27] neg_lo:[0,1] neg_hi:[0,1]
	v_pk_add_f32 v[30:31], v[28:29], v[30:31] neg_lo:[0,1] neg_hi:[0,1]
	v_pk_add_f32 v[28:29], v[32:33], v[14:15]
	v_pk_add_f32 v[24:25], v[34:35], v[10:11]
	v_pk_add_f32 v[20:21], v[36:37], v[4:5]
	v_pk_add_f32 v[16:17], v[38:39], v[2:3]
	v_pk_add_f32 v[14:15], v[32:33], v[14:15] neg_lo:[0,1] neg_hi:[0,1]
	v_pk_add_f32 v[34:35], v[34:35], v[10:11] neg_lo:[0,1] neg_hi:[0,1]
	v_pk_add_f32 v[36:37], v[36:37], v[4:5] neg_lo:[0,1] neg_hi:[0,1]
	v_pk_add_f32 v[2:3], v[38:39], v[2:3] neg_lo:[0,1] neg_hi:[0,1]
	v_pk_add_f32 v[38:39], v[0:1], v[18:19] op_sel:[0,1] op_sel_hi:[1,0] neg_hi:[0,1]
	v_pk_add_f32 v[4:5], v[6:7], v[22:23] op_sel:[0,1] op_sel_hi:[1,0] neg_hi:[0,1]
	v_pk_add_f32 v[10:11], v[8:9], v[26:27] op_sel:[0,1] op_sel_hi:[1,0] neg_hi:[0,1]
	v_pk_add_f32 v[32:33], v[12:13], v[30:31] op_sel:[0,1] op_sel_hi:[1,0] neg_hi:[0,1]
	v_pk_add_f32 v[0:1], v[0:1], v[18:19] op_sel:[0,1] op_sel_hi:[1,0] neg_lo:[0,1]
	v_pk_add_f32 v[6:7], v[6:7], v[22:23] op_sel:[0,1] op_sel_hi:[1,0] neg_lo:[0,1]
	v_pk_add_f32 v[26:27], v[8:9], v[26:27] op_sel:[0,1] op_sel_hi:[1,0] neg_lo:[0,1]
	v_pk_add_f32 v[12:13], v[12:13], v[30:31] op_sel:[0,1] op_sel_hi:[1,0] neg_lo:[0,1]
	v_pk_add_f32 v[30:31], v[28:29], v[20:21]
	v_pk_mul_f32 v[8:9], v[4:5], s[70:71] op_sel_hi:[1,0]
	v_pk_mul_f32 v[22:23], v[34:35], s[72:73] op_sel_hi:[1,0]
	v_pk_mul_f32 v[18:19], v[6:7], s[64:65] op_sel_hi:[1,0]
	v_pk_add_f32 v[28:29], v[28:29], v[20:21] neg_lo:[0,1] neg_hi:[0,1]
	v_pk_fma_f32 v[4:5], v[4:5], s[44:45], v[8:9] op_sel:[0,0,1] op_sel_hi:[1,0,0] neg_lo:[0,0,1]
	v_pk_fma_f32 v[34:35], v[34:35], s[76:77], v[22:23] op_sel:[0,0,1] op_sel_hi:[1,0,0] neg_lo:[0,0,1]
	v_pk_fma_f32 v[18:19], v[6:7], s[82:83], v[18:19] op_sel:[0,0,1] op_sel_hi:[1,0,0] neg_lo:[0,0,1]
	v_pk_add_f32 v[6:7], v[24:25], v[16:17]
	v_pk_fma_f32 v[22:23], v[10:11], s[72:73], v[38:39] op_sel:[0,0,1] op_sel_hi:[1,0,0] neg_hi:[0,0,1]
	v_pk_add_f32 v[8:9], v[14:15], v[36:37] op_sel:[0,1] op_sel_hi:[1,0] neg_hi:[0,1]
	v_pk_fma_f32 v[20:21], v[26:27], s[72:73], v[0:1] op_sel:[0,0,1] op_sel_hi:[1,0,0] neg_hi:[0,0,1]
	v_pk_add_f32 v[16:17], v[24:25], v[16:17] neg_lo:[0,1] neg_hi:[0,1]
	v_pk_fma_f32 v[10:11], v[10:11], s[76:77], v[22:23] op_sel:[0,0,1] op_sel_hi:[1,0,0] neg_lo:[0,0,1]
	v_pk_add_f32 v[14:15], v[14:15], v[36:37] op_sel:[0,1] op_sel_hi:[1,0] neg_lo:[0,1]
	v_pk_fma_f32 v[26:27], v[26:27], s[72:73], v[20:21] op_sel:[0,0,1] op_sel_hi:[1,0,0] neg_lo:[0,0,1]
	v_pk_add_f32 v[20:21], v[30:31], v[6:7]
	v_pk_fma_f32 v[38:39], v[38:39], s[100:101], v[10:11] op_sel_hi:[1,0,1] neg_lo:[0,0,1] neg_hi:[0,0,1]
	v_pk_fma_f32 v[36:37], v[2:3], s[72:73], v[34:35] op_sel:[0,0,1] op_sel_hi:[1,0,0] neg_hi:[0,0,1]
	v_pk_fma_f32 v[0:1], v[0:1], s[100:101], v[26:27] op_sel_hi:[1,0,1] neg_lo:[0,0,1] neg_hi:[0,0,1]
	v_pk_add_f32 v[30:31], v[30:31], v[6:7] neg_lo:[0,1] neg_hi:[0,1]
	v_pk_fma_f32 v[6:7], v[32:33], s[64:65], v[4:5] op_sel:[0,0,1] op_sel_hi:[1,0,0] neg_hi:[0,0,1]
	v_pk_fma_f32 v[2:3], v[2:3], s[72:73], v[36:37] op_sel:[0,0,1] op_sel_hi:[1,0,0] neg_lo:[0,0,1]
	v_pk_fma_f32 v[36:37], v[12:13], s[82:83], v[18:19] op_sel:[0,0,1] op_sel_hi:[1,0,0] neg_hi:[0,0,1]
	v_pk_add_f32 v[22:23], v[28:29], v[16:17] op_sel:[0,1] op_sel_hi:[1,0] neg_hi:[0,1]
	v_pk_fma_f32 v[6:7], v[32:33], s[82:83], v[6:7] op_sel:[0,0,1] op_sel_hi:[1,0,0] neg_lo:[0,0,1]
	v_pk_fma_f32 v[34:35], v[34:35], s[100:101], v[2:3] op_sel_hi:[1,0,1] neg_lo:[0,0,1] neg_hi:[0,0,1]
	v_pk_fma_f32 v[36:37], v[12:13], s[64:65], v[36:37] op_sel:[0,0,1] op_sel_hi:[1,0,0] neg_lo:[0,0,1]
	v_pk_add_f32 v[16:17], v[28:29], v[16:17] op_sel:[0,1] op_sel_hi:[1,0] neg_lo:[0,1]
	v_pk_fma_f32 v[4:5], v[4:5], s[100:101], v[6:7] op_sel_hi:[1,0,1] neg_lo:[0,0,1] neg_hi:[0,0,1]
	v_pk_add_f32 v[28:29], v[8:9], v[2:3]
	v_pk_fma_f32 v[18:19], v[18:19], s[100:101], v[36:37] op_sel_hi:[1,0,1] neg_lo:[0,0,1] neg_hi:[0,0,1]
	v_pk_add_f32 v[12:13], v[10:11], v[6:7]
; template <bool INV> __device__ __forceinline__ void bfly16_tab(f32x2 (&x)[16], const LAS f32x2* T, int tstride, int j) {
;     ...
;     if (!INV) {
; #pragma unroll
;         for (int r = 1; r < 16; ++r) { const f32x2 p = T[r * tstride + j]; x[4 * (r & 3) + (r >> 2)] = cmul(x[4 * (r & 3) + (r >> 2)], p); } }
; }
; template <bool INV> __device__ __forceinline__ void pass16_s64(LAS f32x2* X, const LAS f32x2* TH, int base, int j) {
;     f32x2 x[16];
; #pragma unroll
;     for (int q = 0; q < 16; ++q) x[q] = X[base + q * 68];
;     bfly16_tab<INV>(x, TH - 2048, 64, j);
; #pragma unroll
;     for (int c = 0; c < 4; ++c)
; #pragma unroll
;         for (int d = 0; d < 4; ++d) X[base + (c + 4 * d) * 68] = x[4 * c + d];
; }
; template <bool INV> __device__ __forceinline__ void pass16(LAS f32x2* X, const LAS f32x2* TH, const LAS f32x2* TL, int base, int stride, int tw) {
;     f32x2 x[16];
; #pragma unroll
;     for (int q = 0; q < 16; ++q) x[q] = X[base + q * stride];
;     bfly16<INV>(x, TH, TL, tw);
; #pragma unroll
;     for (int c = 0; c < 4; ++c)
; #pragma unroll
;         for (int d = 0; d < 4; ++d) X[base + (c + 4 * d) * stride] = x[4 * c + d];
; }
; template <bool INV> __device__ __forceinline__ void pass16_s4(LAS f32x2* X, const LAS f32x2* TH, const LAS f32x2* TL, int tid) {
; #pragma unroll 1
;     for (int s = 0; s < 2; ++s) {
;         const int b = tid + NTHR * s, blk = b >> 2, jj = b & 3;
;         LAS f32x2* P = X + blk * 68 + jj;
;         f32x2 x[16];
; #pragma unroll
;         for (int q = 0; q < 16; ++q) x[q] = P[4 * q];
;         bfly16_tab<INV>(x, TH - 1024, 4, jj);
; #pragma unroll
;         for (int c = 0; c < 4; ++c)
; #pragma unroll
;             for (int d = 0; d < 4; ++d) P[4 * (c + 4 * d)] = x[4 * c + d];
;     }
; }
; __device__ __forceinline__ void hyena_latent(Frame& F, int l, int ch, LAS f32x2* X, const LAS f32x2* TH, const LAS f32x2* TL, GAS f32x2* KS, const LAS float* CT  , bool wr = true) {
;     ...
; #pragma unroll
;             for (int i = 0; i < 8; ++i) { const int b = LT() + NTHR * i; const LAS f32x4* P = (const LAS f32x4*)(X + 4 * b + ((b >> 4) << 2)); const f32x4 u = P[0], v = P[1];
;                 f32x2 x0 = {u.x, u.y}, x1 = {u.z, u.w}, x2 = {v.x, v.y}, x3 = {v.z, v.w}; r4<false>(x0, x1, x2, x3);
;                 kreg[2 * i] = (f32x4){x0.x, x0.y, x1.x, x1.y}; kreg[2 * i + 1] = (f32x4){x2.x, x2.y, x3.x, x3.y}; }
	v_pk_add_f32 v[8:9], v[8:9], v[2:3] neg_lo:[0,1] neg_hi:[0,1]
	v_pk_add_f32 v[2:3], v[26:27], v[36:37]
	v_pk_add_f32 v[6:7], v[10:11], v[6:7] neg_lo:[0,1] neg_hi:[0,1]
	v_pk_add_f32 v[10:11], v[14:15], v[34:35] op_sel:[0,1] op_sel_hi:[1,0] neg_hi:[0,1]
	v_pk_add_f32 v[26:27], v[26:27], v[36:37] neg_lo:[0,1] neg_hi:[0,1]
	v_pk_add_f32 v[36:37], v[38:39], v[4:5] op_sel:[0,1] op_sel_hi:[1,0] neg_hi:[0,1]
	v_pk_add_f32 v[34:35], v[14:15], v[34:35] op_sel:[0,1] op_sel_hi:[1,0] neg_lo:[0,1]
	v_pk_add_f32 v[14:15], v[0:1], v[18:19] op_sel:[0,1] op_sel_hi:[1,0] neg_hi:[0,1]
	v_pk_add_f32 v[38:39], v[38:39], v[4:5] op_sel:[0,1] op_sel_hi:[1,0] neg_lo:[0,1]
	v_pk_add_f32 v[18:19], v[0:1], v[18:19] op_sel:[0,1] op_sel_hi:[1,0] neg_lo:[0,1]
	v_pk_mul_f32 v[0:1], v[12:13], v[232:233] op_sel:[0,1] op_sel_hi:[1,1]
	v_pk_mul_f32 v[4:5], v[28:29], v[234:235] op_sel:[0,1] op_sel_hi:[1,1]
	v_pk_fma_f32 v[0:1], v[12:13], v[232:233], v[0:1] op_sel:[0,0,1] op_sel_hi:[1,0,0] neg_lo:[0,0,1]
	v_pk_mul_f32 v[12:13], v[2:3], v[208:209] op_sel:[0,1] op_sel_hi:[1,1]
	v_pk_fma_f32 v[28:29], v[28:29], v[234:235], v[4:5] op_sel:[0,0,1] op_sel_hi:[1,0,0] neg_lo:[0,0,1]
	v_pk_mul_f32 v[4:5], v[22:23], v[210:211] op_sel:[0,1] op_sel_hi:[1,1]
	v_pk_fma_f32 v[12:13], v[2:3], v[208:209], v[12:13] op_sel:[0,0,1] op_sel_hi:[1,0,0] neg_lo:[0,0,1]
	v_pk_mul_f32 v[2:3], v[36:37], v[204:205] op_sel:[0,1] op_sel_hi:[1,1]
	v_pk_fma_f32 v[4:5], v[22:23], v[210:211], v[4:5] op_sel:[0,0,1] op_sel_hi:[1,0,0] neg_lo:[0,0,1]
	v_pk_mul_f32 v[22:23], v[10:11], v[206:207] op_sel:[0,1] op_sel_hi:[1,1]
	v_pk_fma_f32 v[2:3], v[36:37], v[204:205], v[2:3] op_sel:[0,0,1] op_sel_hi:[1,0,0] neg_lo:[0,0,1]
	v_pk_mul_f32 v[36:37], v[14:15], v[200:201] op_sel:[0,1] op_sel_hi:[1,1]
	v_pk_fma_f32 v[22:23], v[10:11], v[206:207], v[22:23] op_sel:[0,0,1] op_sel_hi:[1,0,0] neg_lo:[0,0,1]
	v_pk_mul_f32 v[10:11], v[30:31], v[202:203] op_sel:[0,1] op_sel_hi:[1,1]
	v_pk_fma_f32 v[36:37], v[14:15], v[200:201], v[36:37] op_sel:[0,0,1] op_sel_hi:[1,0,0] neg_lo:[0,0,1]
	v_pk_mul_f32 v[14:15], v[6:7], v[196:197] op_sel:[0,1] op_sel_hi:[1,1]
	v_pk_fma_f32 v[30:31], v[30:31], v[202:203], v[10:11] op_sel:[0,0,1] op_sel_hi:[1,0,0] neg_lo:[0,0,1]
	v_pk_mul_f32 v[10:11], v[8:9], v[198:199] op_sel:[0,1] op_sel_hi:[1,1]
	v_pk_fma_f32 v[14:15], v[6:7], v[196:197], v[14:15] op_sel:[0,0,1] op_sel_hi:[1,0,0] neg_lo:[0,0,1]
	v_pk_mul_f32 v[6:7], v[26:27], v[192:193] op_sel:[0,1] op_sel_hi:[1,1]
	v_pk_fma_f32 v[10:11], v[8:9], v[198:199], v[10:11] op_sel:[0,0,1] op_sel_hi:[1,0,0] neg_lo:[0,0,1]
	v_pk_mul_f32 v[8:9], v[16:17], v[194:195] op_sel:[0,1] op_sel_hi:[1,1]
	v_pk_fma_f32 v[26:27], v[26:27], v[192:193], v[6:7] op_sel:[0,0,1] op_sel_hi:[1,0,0] neg_lo:[0,0,1]
	v_pk_mul_f32 v[6:7], v[38:39], v[188:189] op_sel:[0,1] op_sel_hi:[1,1]
	v_pk_fma_f32 v[16:17], v[16:17], v[194:195], v[8:9] op_sel:[0,0,1] op_sel_hi:[1,0,0] neg_lo:[0,0,1]
	v_pk_mul_f32 v[8:9], v[34:35], v[190:191] op_sel:[0,1] op_sel_hi:[1,1]
	v_pk_fma_f32 v[38:39], v[38:39], v[188:189], v[6:7] op_sel:[0,0,1] op_sel_hi:[1,0,0] neg_lo:[0,0,1]
	v_pk_mul_f32 v[6:7], v[18:19], v[186:187] op_sel:[0,1] op_sel_hi:[1,1]
	v_pk_fma_f32 v[8:9], v[34:35], v[190:191], v[8:9] op_sel:[0,0,1] op_sel_hi:[1,0,0] neg_lo:[0,0,1]
	v_pk_fma_f32 v[18:19], v[18:19], v[186:187], v[6:7] op_sel:[0,0,1] op_sel_hi:[1,0,0] neg_lo:[0,0,1]
	ds_write_b64 v151, v[20:21] offset:0
	ds_write_b64 v151, v[0:1] offset:32
	ds_write_b64 v151, v[28:29] offset:64
	ds_write_b64 v151, v[12:13] offset:96
	ds_write_b64 v151, v[4:5] offset:128
	ds_write_b64 v151, v[2:3] offset:160
	ds_write_b64 v151, v[22:23] offset:192
	ds_write_b64 v151, v[36:37] offset:224
	ds_write_b64 v151, v[30:31] offset:256
	ds_write_b64 v151, v[14:15] offset:288
	ds_write_b64 v151, v[10:11] offset:320
	ds_write_b64 v151, v[26:27] offset:352
	ds_write_b64 v151, v[16:17] offset:384
	ds_write_b64 v151, v[38:39] offset:416
	ds_write_b64 v151, v[8:9] offset:448
	ds_write_b64 v151, v[18:19] offset:480
	s_cbranch_scc1 .LBB0_700
	v_mov_b32_e32 v0, v140
	s_waitcnt lgkmcnt(0)
	s_barrier
	v_mov_b32_e32 v128, v140
	v_lshlrev_b32_e32 v1, 5, v0
	v_lshlrev_b32_e32 v0, 1, v0
	v_and_b32_e32 v0, 0xffffffe0, v0
	v_add3_u32 v0, 0, v1, v0
	ds_read_b128 v[56:59], v0
	ds_read_b128 v[60:63], v0 offset:16
	v_mov_b32_e32 v0, v140
	s_and_b64 vcc, s[26:27], exec
	v_add_u32_e32 v0, 0x200, v0
	v_lshlrev_b32_e32 v1, 5, v0
	v_lshlrev_b32_e32 v0, 1, v0
	v_and_b32_e32 v0, 0xffffffe0, v0
	v_add3_u32 v0, 0, v1, v0
	ds_read_b128 v[48:51], v0
	ds_read_b128 v[52:55], v0 offset:16
	v_mov_b32_e32 v0, v140
	s_nop 0
	v_add_u32_e32 v0, 0x400, v0
	v_lshlrev_b32_e32 v1, 5, v0
	v_lshlrev_b32_e32 v0, 1, v0
	v_and_b32_e32 v0, 0xffffffe0, v0
	v_add3_u32 v0, 0, v1, v0
	ds_read_b128 v[40:43], v0
	ds_read_b128 v[44:47], v0 offset:16
	v_mov_b32_e32 v0, v140
	s_nop 0
	v_add_u32_e32 v0, 0x600, v0
	v_lshlrev_b32_e32 v1, 5, v0
	v_lshlrev_b32_e32 v0, 1, v0
	v_and_b32_e32 v0, 0xffffffe0, v0
	v_add3_u32 v0, 0, v1, v0
	ds_read_b128 v[32:35], v0
	ds_read_b128 v[36:39], v0 offset:16
	v_mov_b32_e32 v0, v140
	s_nop 0
	v_add_u32_e32 v0, 0x800, v0
	v_lshlrev_b32_e32 v1, 5, v0
	v_lshlrev_b32_e32 v0, 1, v0
	v_and_b32_e32 v0, 0xffffffe0, v0
	v_add3_u32 v0, 0, v1, v0
	ds_read_b128 v[24:27], v0
	ds_read_b128 v[28:31], v0 offset:16
	v_mov_b32_e32 v0, v140
	s_nop 0
	v_add_u32_e32 v0, 0xa00, v0
	v_lshlrev_b32_e32 v1, 5, v0
	v_lshlrev_b32_e32 v0, 1, v0
	v_and_b32_e32 v0, 0xffffffe0, v0
	v_add3_u32 v0, 0, v1, v0
	ds_read_b128 v[12:15], v0
	ds_read_b128 v[20:23], v0 offset:16
	v_mov_b32_e32 v0, v140
	s_nop 0
	v_add_u32_e32 v0, 0xc00, v0
	v_lshlrev_b32_e32 v1, 5, v0
	v_lshlrev_b32_e32 v0, 1, v0
	v_and_b32_e32 v0, 0xffffffe0, v0
	v_add3_u32 v0, 0, v1, v0
	ds_read_b128 v[4:7], v0
	ds_read_b128 v[16:19], v0 offset:16
	v_mov_b32_e32 v0, v140
	s_nop 0
	v_add_u32_e32 v0, 0xe00, v0
	v_lshlrev_b32_e32 v1, 5, v0
	v_lshlrev_b32_e32 v0, 1, v0
	v_and_b32_e32 v0, 0xffffffe0, v0
	v_add3_u32 v8, 0, v1, v0
	ds_read_b128 v[0:3], v8
	ds_read_b128 v[8:11], v8 offset:16
	s_waitcnt lgkmcnt(0)
	s_nop 0
	s_nop 0
	v_lshlrev_b32_e32 v176, 2, v128
	s_cbranch_vccz .LBB0_715
	s_waitcnt vmcnt(15)
	v_mov_b32_dpp v134, v127 wave_shr:1 row_mask:0xf bank_mask:0xf
	v_mov_b32_dpp v133, v124 wave_shl:1 row_mask:0xf bank_mask:0xf
	s_waitcnt vmcnt(14)
	v_mov_b32_dpp v130, v123 wave_shr:1 row_mask:0xf bank_mask:0xf
	v_mov_b32_dpp v129, v120 wave_shl:1 row_mask:0xf bank_mask:0xf
	s_and_saveexec_b64 s[36:37], s[8:9]
	s_cbranch_execz .LBB0_708
	v_cmp_lt_i32_e32 vcc, 0, v176
	s_waitcnt lgkmcnt(1)
	v_mov_b32_e32 v130, 0
	v_mov_b32_e32 v134, 0
	s_and_saveexec_b64 s[38:39], vcc
	s_cbranch_execz .LBB0_705
	v_lshl_add_u64 v[134:135], v[176:177], 2, s[20:21]
	global_load_dword v134, v[134:135], off offset:-4

; #define LAS __attribute__((address_space(3)))
; __device__ __forceinline__ f32x2 cmul(f32x2 a, f32x2 b) { return (f32x2){a.x * b.x - a.y * b.y, a.x * b.y + a.y * b.x}; }
; __device__ __forceinline__ float lane_read(float v, int src_lane) { return __builtin_bit_cast(float, __builtin_amdgcn_ds_bpermute(src_lane << 2, __builtin_bit_cast(int, v))); }
; #define LT() ({ int lt_ = tid; asm volatile("" : "+v"(lt_)); lt_; })
; __device__ __forceinline__ void hyena_latent(Frame& F, int l, int ch, LAS f32x2* X, const LAS f32x2* TH, const LAS f32x2* TL, GAS f32x2* KS, const LAS float* CT  , bool wr = true) {
;     ...
;             for (int i = 0; i < 8; ++i) { const int g = LT() + NTHR * i, n0 = 4 * g;
;                 f32x4 z0 = pc0[i], z1 = pc1[i];
;                 if (o == 0) { const f32x4 c = pc0[i], d = pc1[i]; const int ln = F.lane;
;                     float l0 = lane_read(c.w, ln - 1), r0 = lane_read(c.x, ln + 1), l1 = lane_read(d.w, ln - 1), r1 = lane_read(d.x, ln + 1);
;                     if (ln == 0) { l0 = n0 > 0 ? hv[n0 - 1] : 0.f; l1 = n0 > 0 ? hv[SEQ + n0 - 1] : 0.f; }
;                     if (ln == 63) { r0 = n0 + 4 < SEQ ? hv[n0 + 4] : 0.f; r1 = n0 + 4 < SEQ ? hv[SEQ + n0 + 4] : 0.f; }
;                     z0 = (f32x4){vw0 * l0 + vw1 * c.x + vw2 * c.y + vbb, vw0 * c.x + vw1 * c.y + vw2 * c.z + vbb, vw0 * c.y + vw1 * c.z + vw2 * c.w + vbb, vw0 * c.z + vw1 * c.w + vw2 * r0 + vbb};
;                     z1 = (f32x4){vw0 * l1 + vw1 * d.x + vw2 * d.y + vbb, vw0 * d.x + vw1 * d.y + vw2 * d.z + vbb, vw0 * d.y + vw1 * d.z + vw2 * d.w + vbb, vw0 * d.z + vw1 * d.w + vw2 * r1 + vbb}; }
;                 LAS f32x4* XP = (LAS f32x4*)(X + phys(n0));
;                 if (par == 0) { XP[0] = (f32x4){z0.x, z1.x, z0.y, z1.y}; XP[1] = (f32x4){z0.z, z1.z, z0.w, z1.w}; }
;                 else { f32x2 w[4]; tw4(TH, TL, n0, w);
;                     const f32x2 a0 = cmul((f32x2){z0.x, z1.x}, w[0]), a1 = cmul((f32x2){z0.y, z1.y}, w[1]), a2 = cmul((f32x2){z0.z, z1.z}, w[2]), a3 = cmul((f32x2){z0.w, z1.w}, w[3]);
;                     XP[0] = (f32x4){a0.x, a0.y, a1.x, a1.y}; XP[1] = (f32x4){a2.x, a2.y, a3.x, a3.y}; } }
.LBB0_719:
	s_waitcnt vmcnt(14)
	v_ashrrev_i32_e32 v120, 4, v176
	v_lshlrev_b32_e32 v120, 3, v120
	v_and_b32_e32 v120, 0xffffffe0, v120
	v_lshlrev_b32_e32 v121, 3, v176
	v_add3_u32 v120, 0, v120, v121
	ds_write_b128 v120, v[128:131]
	ds_write_b128 v120, v[132:135] offset:16
	v_mov_b32_e32 v120, v140
	s_andn2_b64 vcc, exec, s[26:27]
	v_lshlrev_b32_e32 v130, 2, v120
	v_cndmask_b32_e64 v120, 0, 1, s[26:27]
	v_cmp_ne_u32_e64 s[14:15], 1, v120
	v_add_u32_e32 v176, 0x800, v130
	s_cbranch_vccnz .LBB0_733
	s_waitcnt vmcnt(13)
	v_mov_b32_dpp v126, v119 wave_shr:1 row_mask:0xf bank_mask:0xf
	v_mov_b32_dpp v125, v116 wave_shl:1 row_mask:0xf bank_mask:0xf
	s_waitcnt vmcnt(12)
	v_mov_b32_dpp v122, v115 wave_shr:1 row_mask:0xf bank_mask:0xf
	v_mov_b32_dpp v121, v112 wave_shl:1 row_mask:0xf bank_mask:0xf
	s_and_saveexec_b64 s[36:37], s[8:9]
	s_cbranch_execz .LBB0_726
	v_cmp_lt_i32_e32 vcc, 0, v176
	s_waitcnt lgkmcnt(1)
	v_mov_b32_e32 v122, 0
	v_mov_b32_e32 v126, 0
	s_and_saveexec_b64 s[38:39], vcc
	s_cbranch_execz .LBB0_723
	v_lshl_add_u64 v[126:127], v[176:177], 2, s[20:21]
	global_load_dword v126, v[126:127], off offset:-4

; #define LAS __attribute__((address_space(3)))
; __device__ __forceinline__ f32x2 cmul(f32x2 a, f32x2 b) { return (f32x2){a.x * b.x - a.y * b.y, a.x * b.y + a.y * b.x}; }
; __device__ __forceinline__ float lane_read(float v, int src_lane) { return __builtin_bit_cast(float, __builtin_amdgcn_ds_bpermute(src_lane << 2, __builtin_bit_cast(int, v))); }
; #define LT() ({ int lt_ = tid; asm volatile("" : "+v"(lt_)); lt_; })
; __device__ __forceinline__ void hyena_latent(Frame& F, int l, int ch, LAS f32x2* X, const LAS f32x2* TH, const LAS f32x2* TL, GAS f32x2* KS, const LAS float* CT  , bool wr = true) {
;     ...
;             for (int i = 0; i < 8; ++i) { const int g = LT() + NTHR * i, n0 = 4 * g;
;                 f32x4 z0 = pc0[i], z1 = pc1[i];
;                 if (o == 0) { const f32x4 c = pc0[i], d = pc1[i]; const int ln = F.lane;
;                     float l0 = lane_read(c.w, ln - 1), r0 = lane_read(c.x, ln + 1), l1 = lane_read(d.w, ln - 1), r1 = lane_read(d.x, ln + 1);
;                     if (ln == 0) { l0 = n0 > 0 ? hv[n0 - 1] : 0.f; l1 = n0 > 0 ? hv[SEQ + n0 - 1] : 0.f; }
;                     if (ln == 63) { r0 = n0 + 4 < SEQ ? hv[n0 + 4] : 0.f; r1 = n0 + 4 < SEQ ? hv[SEQ + n0 + 4] : 0.f; }
;                     z0 = (f32x4){vw0 * l0 + vw1 * c.x + vw2 * c.y + vbb, vw0 * c.x + vw1 * c.y + vw2 * c.z + vbb, vw0 * c.y + vw1 * c.z + vw2 * c.w + vbb, vw0 * c.z + vw1 * c.w + vw2 * r0 + vbb};
;                     z1 = (f32x4){vw0 * l1 + vw1 * d.x + vw2 * d.y + vbb, vw0 * d.x + vw1 * d.y + vw2 * d.z + vbb, vw0 * d.y + vw1 * d.z + vw2 * d.w + vbb, vw0 * d.z + vw1 * d.w + vw2 * r1 + vbb}; }
;                 LAS f32x4* XP = (LAS f32x4*)(X + phys(n0));
;                 if (par == 0) { XP[0] = (f32x4){z0.x, z1.x, z0.y, z1.y}; XP[1] = (f32x4){z0.z, z1.z, z0.w, z1.w}; }
;                 else { f32x2 w[4]; tw4(TH, TL, n0, w);
;                     const f32x2 a0 = cmul((f32x2){z0.x, z1.x}, w[0]), a1 = cmul((f32x2){z0.y, z1.y}, w[1]), a2 = cmul((f32x2){z0.z, z1.z}, w[2]), a3 = cmul((f32x2){z0.w, z1.w}, w[3]);
;                     XP[0] = (f32x4){a0.x, a0.y, a1.x, a1.y}; XP[1] = (f32x4){a2.x, a2.y, a3.x, a3.y}; } }
.LBB0_737:
	s_waitcnt vmcnt(12)
	v_ashrrev_i32_e32 v112, 4, v176
	v_lshlrev_b32_e32 v112, 3, v112
	v_and_b32_e32 v112, 0xffffffe0, v112
	v_lshlrev_b32_e32 v113, 3, v130
	v_add3_u32 v112, 0, v112, v113
	ds_write_b128 v112, v[120:123] offset:16384
	ds_write_b128 v112, v[124:127] offset:16400
	v_mov_b32_e32 v112, v140
	s_and_b64 vcc, exec, s[14:15]
	v_lshlrev_b32_e32 v122, 2, v112
	v_add_u32_e32 v176, 0x1000, v122
	s_cbranch_vccnz .LBB0_751
	s_waitcnt vmcnt(11)
	v_mov_b32_dpp v118, v111 wave_shr:1 row_mask:0xf bank_mask:0xf
	v_mov_b32_dpp v117, v108 wave_shl:1 row_mask:0xf bank_mask:0xf
	s_waitcnt vmcnt(10)
	v_mov_b32_dpp v114, v107 wave_shr:1 row_mask:0xf bank_mask:0xf
	v_mov_b32_dpp v113, v104 wave_shl:1 row_mask:0xf bank_mask:0xf
	s_and_saveexec_b64 s[36:37], s[8:9]
	s_cbranch_execz .LBB0_744
	v_cmp_lt_i32_e32 vcc, 0, v176
	s_waitcnt lgkmcnt(1)
	v_mov_b32_e32 v114, 0
	v_mov_b32_e32 v118, 0
	s_and_saveexec_b64 s[38:39], vcc
	s_cbranch_execz .LBB0_741
	v_lshl_add_u64 v[118:119], v[176:177], 2, s[20:21]
	global_load_dword v118, v[118:119], off offset:-4

; #define LAS __attribute__((address_space(3)))
; __device__ __forceinline__ f32x2 cmul(f32x2 a, f32x2 b) { return (f32x2){a.x * b.x - a.y * b.y, a.x * b.y + a.y * b.x}; }
; __device__ __forceinline__ float lane_read(float v, int src_lane) { return __builtin_bit_cast(float, __builtin_amdgcn_ds_bpermute(src_lane << 2, __builtin_bit_cast(int, v))); }
; #define LT() ({ int lt_ = tid; asm volatile("" : "+v"(lt_)); lt_; })
; __device__ __forceinline__ void hyena_latent(Frame& F, int l, int ch, LAS f32x2* X, const LAS f32x2* TH, const LAS f32x2* TL, GAS f32x2* KS, const LAS float* CT  , bool wr = true) {
;     ...
;             for (int i = 0; i < 8; ++i) { const int g = LT() + NTHR * i, n0 = 4 * g;
;                 f32x4 z0 = pc0[i], z1 = pc1[i];
;                 if (o == 0) { const f32x4 c = pc0[i], d = pc1[i]; const int ln = F.lane;
;                     float l0 = lane_read(c.w, ln - 1), r0 = lane_read(c.x, ln + 1), l1 = lane_read(d.w, ln - 1), r1 = lane_read(d.x, ln + 1);
;                     if (ln == 0) { l0 = n0 > 0 ? hv[n0 - 1] : 0.f; l1 = n0 > 0 ? hv[SEQ + n0 - 1] : 0.f; }
;                     if (ln == 63) { r0 = n0 + 4 < SEQ ? hv[n0 + 4] : 0.f; r1 = n0 + 4 < SEQ ? hv[SEQ + n0 + 4] : 0.f; }
;                     z0 = (f32x4){vw0 * l0 + vw1 * c.x + vw2 * c.y + vbb, vw0 * c.x + vw1 * c.y + vw2 * c.z + vbb, vw0 * c.y + vw1 * c.z + vw2 * c.w + vbb, vw0 * c.z + vw1 * c.w + vw2 * r0 + vbb};
;                     z1 = (f32x4){vw0 * l1 + vw1 * d.x + vw2 * d.y + vbb, vw0 * d.x + vw1 * d.y + vw2 * d.z + vbb, vw0 * d.y + vw1 * d.z + vw2 * d.w + vbb, vw0 * d.z + vw1 * d.w + vw2 * r1 + vbb}; }
;                 LAS f32x4* XP = (LAS f32x4*)(X + phys(n0));
;                 if (par == 0) { XP[0] = (f32x4){z0.x, z1.x, z0.y, z1.y}; XP[1] = (f32x4){z0.z, z1.z, z0.w, z1.w}; }
;                 else { f32x2 w[4]; tw4(TH, TL, n0, w);
;                     const f32x2 a0 = cmul((f32x2){z0.x, z1.x}, w[0]), a1 = cmul((f32x2){z0.y, z1.y}, w[1]), a2 = cmul((f32x2){z0.z, z1.z}, w[2]), a3 = cmul((f32x2){z0.w, z1.w}, w[3]);
;                     XP[0] = (f32x4){a0.x, a0.y, a1.x, a1.y}; XP[1] = (f32x4){a2.x, a2.y, a3.x, a3.y}; } }
.LBB0_755:
	s_waitcnt vmcnt(10)
	v_ashrrev_i32_e32 v104, 4, v176
	v_lshlrev_b32_e32 v104, 3, v104
	v_and_b32_e32 v104, 0xffffffe0, v104
	v_lshlrev_b32_e32 v105, 3, v122
	v_add3_u32 v104, 0, v104, v105
	ds_write_b128 v104, v[112:115] offset:32768
	ds_write_b128 v104, v[116:119] offset:32784
	v_mov_b32_e32 v104, v140
	s_and_b64 vcc, exec, s[14:15]
	v_lshlrev_b32_e32 v114, 2, v104
	v_add_u32_e32 v176, 0x1800, v114
	s_cbranch_vccnz .LBB0_769
	s_waitcnt vmcnt(9)
	v_mov_b32_dpp v110, v103 wave_shr:1 row_mask:0xf bank_mask:0xf
	v_mov_b32_dpp v109, v100 wave_shl:1 row_mask:0xf bank_mask:0xf
	s_waitcnt vmcnt(8)
	v_mov_b32_dpp v106, v99 wave_shr:1 row_mask:0xf bank_mask:0xf
	v_mov_b32_dpp v105, v96 wave_shl:1 row_mask:0xf bank_mask:0xf
	s_and_saveexec_b64 s[36:37], s[8:9]
	s_cbranch_execz .LBB0_762
	v_cmp_lt_i32_e32 vcc, 0, v176
	s_waitcnt lgkmcnt(1)
	v_mov_b32_e32 v106, 0
	v_mov_b32_e32 v110, 0
	s_and_saveexec_b64 s[38:39], vcc
	s_cbranch_execz .LBB0_759
	v_lshl_add_u64 v[110:111], v[176:177], 2, s[20:21]
	global_load_dword v110, v[110:111], off offset:-4

; #define LAS __attribute__((address_space(3)))
; __device__ __forceinline__ f32x2 cmul(f32x2 a, f32x2 b) { return (f32x2){a.x * b.x - a.y * b.y, a.x * b.y + a.y * b.x}; }
; __device__ __forceinline__ float lane_read(float v, int src_lane) { return __builtin_bit_cast(float, __builtin_amdgcn_ds_bpermute(src_lane << 2, __builtin_bit_cast(int, v))); }
; #define LT() ({ int lt_ = tid; asm volatile("" : "+v"(lt_)); lt_; })
; __device__ __forceinline__ void hyena_latent(Frame& F, int l, int ch, LAS f32x2* X, const LAS f32x2* TH, const LAS f32x2* TL, GAS f32x2* KS, const LAS float* CT  , bool wr = true) {
;     ...
;             for (int i = 0; i < 8; ++i) { const int g = LT() + NTHR * i, n0 = 4 * g;
;                 f32x4 z0 = pc0[i], z1 = pc1[i];
;                 if (o == 0) { const f32x4 c = pc0[i], d = pc1[i]; const int ln = F.lane;
;                     float l0 = lane_read(c.w, ln - 1), r0 = lane_read(c.x, ln + 1), l1 = lane_read(d.w, ln - 1), r1 = lane_read(d.x, ln + 1);
;                     if (ln == 0) { l0 = n0 > 0 ? hv[n0 - 1] : 0.f; l1 = n0 > 0 ? hv[SEQ + n0 - 1] : 0.f; }
;                     if (ln == 63) { r0 = n0 + 4 < SEQ ? hv[n0 + 4] : 0.f; r1 = n0 + 4 < SEQ ? hv[SEQ + n0 + 4] : 0.f; }
;                     z0 = (f32x4){vw0 * l0 + vw1 * c.x + vw2 * c.y + vbb, vw0 * c.x + vw1 * c.y + vw2 * c.z + vbb, vw0 * c.y + vw1 * c.z + vw2 * c.w + vbb, vw0 * c.z + vw1 * c.w + vw2 * r0 + vbb};
;                     z1 = (f32x4){vw0 * l1 + vw1 * d.x + vw2 * d.y + vbb, vw0 * d.x + vw1 * d.y + vw2 * d.z + vbb, vw0 * d.y + vw1 * d.z + vw2 * d.w + vbb, vw0 * d.z + vw1 * d.w + vw2 * r1 + vbb}; }
;                 LAS f32x4* XP = (LAS f32x4*)(X + phys(n0));
;                 if (par == 0) { XP[0] = (f32x4){z0.x, z1.x, z0.y, z1.y}; XP[1] = (f32x4){z0.z, z1.z, z0.w, z1.w}; }
;                 else { f32x2 w[4]; tw4(TH, TL, n0, w);
;                     const f32x2 a0 = cmul((f32x2){z0.x, z1.x}, w[0]), a1 = cmul((f32x2){z0.y, z1.y}, w[1]), a2 = cmul((f32x2){z0.z, z1.z}, w[2]), a3 = cmul((f32x2){z0.w, z1.w}, w[3]);
;                     XP[0] = (f32x4){a0.x, a0.y, a1.x, a1.y}; XP[1] = (f32x4){a2.x, a2.y, a3.x, a3.y}; } }
.LBB0_773:
	s_waitcnt vmcnt(8)
	v_ashrrev_i32_e32 v96, 4, v176
	v_lshlrev_b32_e32 v96, 3, v96
	v_and_b32_e32 v96, 0xffffffe0, v96
	v_lshlrev_b32_e32 v97, 3, v114
	v_add3_u32 v96, 0, v96, v97
	ds_write_b128 v96, v[104:107] offset:49152
	ds_write_b128 v96, v[108:111] offset:49168
	v_mov_b32_e32 v96, v140
	s_and_b64 vcc, exec, s[14:15]
	v_lshlrev_b32_e32 v106, 2, v96
	v_add_u32_e32 v176, 0x2000, v106
	s_cbranch_vccnz .LBB0_787
	s_waitcnt vmcnt(7)
	v_mov_b32_dpp v102, v95 wave_shr:1 row_mask:0xf bank_mask:0xf
	v_mov_b32_dpp v101, v92 wave_shl:1 row_mask:0xf bank_mask:0xf
	s_waitcnt vmcnt(6)
	v_mov_b32_dpp v98, v91 wave_shr:1 row_mask:0xf bank_mask:0xf
	v_mov_b32_dpp v97, v88 wave_shl:1 row_mask:0xf bank_mask:0xf
	s_and_saveexec_b64 s[36:37], s[8:9]
	s_cbranch_execz .LBB0_780
	v_cmp_lt_i32_e32 vcc, 0, v176
	s_waitcnt lgkmcnt(1)
	v_mov_b32_e32 v98, 0
	v_mov_b32_e32 v102, 0
	s_and_saveexec_b64 s[38:39], vcc
	s_cbranch_execz .LBB0_777
	v_lshl_add_u64 v[102:103], v[176:177], 2, s[20:21]
	global_load_dword v102, v[102:103], off offset:-4

; #define LAS __attribute__((address_space(3)))
; __device__ __forceinline__ f32x2 cmul(f32x2 a, f32x2 b) { return (f32x2){a.x * b.x - a.y * b.y, a.x * b.y + a.y * b.x}; }
; __device__ __forceinline__ float lane_read(float v, int src_lane) { return __builtin_bit_cast(float, __builtin_amdgcn_ds_bpermute(src_lane << 2, __builtin_bit_cast(int, v))); }
; #define LT() ({ int lt_ = tid; asm volatile("" : "+v"(lt_)); lt_; })
; __device__ __forceinline__ void hyena_latent(Frame& F, int l, int ch, LAS f32x2* X, const LAS f32x2* TH, const LAS f32x2* TL, GAS f32x2* KS, const LAS float* CT  , bool wr = true) {
;     ...
;             for (int i = 0; i < 8; ++i) { const int g = LT() + NTHR * i, n0 = 4 * g;
;                 f32x4 z0 = pc0[i], z1 = pc1[i];
;                 if (o == 0) { const f32x4 c = pc0[i], d = pc1[i]; const int ln = F.lane;
;                     float l0 = lane_read(c.w, ln - 1), r0 = lane_read(c.x, ln + 1), l1 = lane_read(d.w, ln - 1), r1 = lane_read(d.x, ln + 1);
;                     if (ln == 0) { l0 = n0 > 0 ? hv[n0 - 1] : 0.f; l1 = n0 > 0 ? hv[SEQ + n0 - 1] : 0.f; }
;                     if (ln == 63) { r0 = n0 + 4 < SEQ ? hv[n0 + 4] : 0.f; r1 = n0 + 4 < SEQ ? hv[SEQ + n0 + 4] : 0.f; }
;                     z0 = (f32x4){vw0 * l0 + vw1 * c.x + vw2 * c.y + vbb, vw0 * c.x + vw1 * c.y + vw2 * c.z + vbb, vw0 * c.y + vw1 * c.z + vw2 * c.w + vbb, vw0 * c.z + vw1 * c.w + vw2 * r0 + vbb};
;                     z1 = (f32x4){vw0 * l1 + vw1 * d.x + vw2 * d.y + vbb, vw0 * d.x + vw1 * d.y + vw2 * d.z + vbb, vw0 * d.y + vw1 * d.z + vw2 * d.w + vbb, vw0 * d.z + vw1 * d.w + vw2 * r1 + vbb}; }
;                 LAS f32x4* XP = (LAS f32x4*)(X + phys(n0));
;                 if (par == 0) { XP[0] = (f32x4){z0.x, z1.x, z0.y, z1.y}; XP[1] = (f32x4){z0.z, z1.z, z0.w, z1.w}; }
;                 else { f32x2 w[4]; tw4(TH, TL, n0, w);
;                     const f32x2 a0 = cmul((f32x2){z0.x, z1.x}, w[0]), a1 = cmul((f32x2){z0.y, z1.y}, w[1]), a2 = cmul((f32x2){z0.z, z1.z}, w[2]), a3 = cmul((f32x2){z0.w, z1.w}, w[3]);
;                     XP[0] = (f32x4){a0.x, a0.y, a1.x, a1.y}; XP[1] = (f32x4){a2.x, a2.y, a3.x, a3.y}; } }
.LBB0_791:
	s_waitcnt vmcnt(6)
	v_ashrrev_i32_e32 v88, 4, v176
	v_lshlrev_b32_e32 v88, 3, v88
	v_and_b32_e32 v88, 0xffffffe0, v88
	v_lshlrev_b32_e32 v89, 3, v176
	v_add3_u32 v88, 0, v88, v89
	ds_write_b128 v88, v[96:99]
	ds_write_b128 v88, v[100:103] offset:16
	v_mov_b32_e32 v88, v140
	s_and_b64 vcc, exec, s[14:15]
	v_lshlrev_b32_e32 v98, 2, v88
	v_add_u32_e32 v176, 0x2800, v98
	s_cbranch_vccnz .LBB0_805
	s_waitcnt vmcnt(5)
	v_mov_b32_dpp v94, v87 wave_shr:1 row_mask:0xf bank_mask:0xf
	v_mov_b32_dpp v93, v84 wave_shl:1 row_mask:0xf bank_mask:0xf
	s_waitcnt vmcnt(4)
	v_mov_b32_dpp v90, v83 wave_shr:1 row_mask:0xf bank_mask:0xf
	v_mov_b32_dpp v89, v80 wave_shl:1 row_mask:0xf bank_mask:0xf
	s_and_saveexec_b64 s[36:37], s[8:9]
	s_cbranch_execz .LBB0_798
	v_cmp_lt_i32_e32 vcc, 0, v176
	s_waitcnt lgkmcnt(1)
	v_mov_b32_e32 v90, 0
	v_mov_b32_e32 v94, 0
	s_and_saveexec_b64 s[38:39], vcc
	s_cbranch_execz .LBB0_795
	v_lshl_add_u64 v[94:95], v[176:177], 2, s[20:21]
	global_load_dword v94, v[94:95], off offset:-4

; #define LAS __attribute__((address_space(3)))
; __device__ __forceinline__ f32x2 cmul(f32x2 a, f32x2 b) { return (f32x2){a.x * b.x - a.y * b.y, a.x * b.y + a.y * b.x}; }
; __device__ __forceinline__ float lane_read(float v, int src_lane) { return __builtin_bit_cast(float, __builtin_amdgcn_ds_bpermute(src_lane << 2, __builtin_bit_cast(int, v))); }
; #define LT() ({ int lt_ = tid; asm volatile("" : "+v"(lt_)); lt_; })
; __device__ __forceinline__ void hyena_latent(Frame& F, int l, int ch, LAS f32x2* X, const LAS f32x2* TH, const LAS f32x2* TL, GAS f32x2* KS, const LAS float* CT  , bool wr = true) {
;     ...
;             for (int i = 0; i < 8; ++i) { const int g = LT() + NTHR * i, n0 = 4 * g;
;                 f32x4 z0 = pc0[i], z1 = pc1[i];
;                 if (o == 0) { const f32x4 c = pc0[i], d = pc1[i]; const int ln = F.lane;
;                     float l0 = lane_read(c.w, ln - 1), r0 = lane_read(c.x, ln + 1), l1 = lane_read(d.w, ln - 1), r1 = lane_read(d.x, ln + 1);
;                     if (ln == 0) { l0 = n0 > 0 ? hv[n0 - 1] : 0.f; l1 = n0 > 0 ? hv[SEQ + n0 - 1] : 0.f; }
;                     if (ln == 63) { r0 = n0 + 4 < SEQ ? hv[n0 + 4] : 0.f; r1 = n0 + 4 < SEQ ? hv[SEQ + n0 + 4] : 0.f; }
;                     z0 = (f32x4){vw0 * l0 + vw1 * c.x + vw2 * c.y + vbb, vw0 * c.x + vw1 * c.y + vw2 * c.z + vbb, vw0 * c.y + vw1 * c.z + vw2 * c.w + vbb, vw0 * c.z + vw1 * c.w + vw2 * r0 + vbb};
;                     z1 = (f32x4){vw0 * l1 + vw1 * d.x + vw2 * d.y + vbb, vw0 * d.x + vw1 * d.y + vw2 * d.z + vbb, vw0 * d.y + vw1 * d.z + vw2 * d.w + vbb, vw0 * d.z + vw1 * d.w + vw2 * r1 + vbb}; }
;                 LAS f32x4* XP = (LAS f32x4*)(X + phys(n0));
;                 if (par == 0) { XP[0] = (f32x4){z0.x, z1.x, z0.y, z1.y}; XP[1] = (f32x4){z0.z, z1.z, z0.w, z1.w}; }
;                 else { f32x2 w[4]; tw4(TH, TL, n0, w);
;                     const f32x2 a0 = cmul((f32x2){z0.x, z1.x}, w[0]), a1 = cmul((f32x2){z0.y, z1.y}, w[1]), a2 = cmul((f32x2){z0.z, z1.z}, w[2]), a3 = cmul((f32x2){z0.w, z1.w}, w[3]);
;                     XP[0] = (f32x4){a0.x, a0.y, a1.x, a1.y}; XP[1] = (f32x4){a2.x, a2.y, a3.x, a3.y}; } }
.LBB0_809:
	s_waitcnt vmcnt(4)
	v_ashrrev_i32_e32 v80, 4, v176
	v_lshlrev_b32_e32 v80, 3, v80
	v_and_b32_e32 v80, 0xffffffe0, v80
	v_lshlrev_b32_e32 v81, 3, v176
	v_add3_u32 v80, 0, v80, v81
	ds_write_b128 v80, v[88:91]
	ds_write_b128 v80, v[92:95] offset:16
	v_mov_b32_e32 v80, v140
	s_and_b64 vcc, exec, s[14:15]
	v_lshlrev_b32_e32 v90, 2, v80
	v_add_u32_e32 v176, 0x3000, v90
	s_cbranch_vccnz .LBB0_823
	s_waitcnt vmcnt(3)
	v_mov_b32_dpp v86, v79 wave_shr:1 row_mask:0xf bank_mask:0xf
	v_mov_b32_dpp v85, v76 wave_shl:1 row_mask:0xf bank_mask:0xf
	s_waitcnt vmcnt(2)
	v_mov_b32_dpp v82, v75 wave_shr:1 row_mask:0xf bank_mask:0xf
	v_mov_b32_dpp v81, v72 wave_shl:1 row_mask:0xf bank_mask:0xf
	s_and_saveexec_b64 s[36:37], s[8:9]
	s_cbranch_execz .LBB0_816
	v_cmp_lt_i32_e32 vcc, 0, v176
	s_waitcnt lgkmcnt(1)
	v_mov_b32_e32 v82, 0
	v_mov_b32_e32 v86, 0
	s_and_saveexec_b64 s[38:39], vcc
	s_cbranch_execz .LBB0_813
	v_lshl_add_u64 v[86:87], v[176:177], 2, s[20:21]
	global_load_dword v86, v[86:87], off offset:-4

; #define LAS __attribute__((address_space(3)))
; __device__ __forceinline__ f32x2 cmul(f32x2 a, f32x2 b) { return (f32x2){a.x * b.x - a.y * b.y, a.x * b.y + a.y * b.x}; }
; __device__ __forceinline__ float lane_read(float v, int src_lane) { return __builtin_bit_cast(float, __builtin_amdgcn_ds_bpermute(src_lane << 2, __builtin_bit_cast(int, v))); }
; #define LT() ({ int lt_ = tid; asm volatile("" : "+v"(lt_)); lt_; })
; __device__ __forceinline__ void hyena_latent(Frame& F, int l, int ch, LAS f32x2* X, const LAS f32x2* TH, const LAS f32x2* TL, GAS f32x2* KS, const LAS float* CT  , bool wr = true) {
;     ...
;             for (int i = 0; i < 8; ++i) { const int g = LT() + NTHR * i, n0 = 4 * g;
;                 f32x4 z0 = pc0[i], z1 = pc1[i];
;                 if (o == 0) { const f32x4 c = pc0[i], d = pc1[i]; const int ln = F.lane;
;                     float l0 = lane_read(c.w, ln - 1), r0 = lane_read(c.x, ln + 1), l1 = lane_read(d.w, ln - 1), r1 = lane_read(d.x, ln + 1);
;                     if (ln == 0) { l0 = n0 > 0 ? hv[n0 - 1] : 0.f; l1 = n0 > 0 ? hv[SEQ + n0 - 1] : 0.f; }
;                     if (ln == 63) { r0 = n0 + 4 < SEQ ? hv[n0 + 4] : 0.f; r1 = n0 + 4 < SEQ ? hv[SEQ + n0 + 4] : 0.f; }
;                     z0 = (f32x4){vw0 * l0 + vw1 * c.x + vw2 * c.y + vbb, vw0 * c.x + vw1 * c.y + vw2 * c.z + vbb, vw0 * c.y + vw1 * c.z + vw2 * c.w + vbb, vw0 * c.z + vw1 * c.w + vw2 * r0 + vbb};
;                     z1 = (f32x4){vw0 * l1 + vw1 * d.x + vw2 * d.y + vbb, vw0 * d.x + vw1 * d.y + vw2 * d.z + vbb, vw0 * d.y + vw1 * d.z + vw2 * d.w + vbb, vw0 * d.z + vw1 * d.w + vw2 * r1 + vbb}; }
;                 LAS f32x4* XP = (LAS f32x4*)(X + phys(n0));
;                 if (par == 0) { XP[0] = (f32x4){z0.x, z1.x, z0.y, z1.y}; XP[1] = (f32x4){z0.z, z1.z, z0.w, z1.w}; }
;                 else { f32x2 w[4]; tw4(TH, TL, n0, w);
;                     const f32x2 a0 = cmul((f32x2){z0.x, z1.x}, w[0]), a1 = cmul((f32x2){z0.y, z1.y}, w[1]), a2 = cmul((f32x2){z0.z, z1.z}, w[2]), a3 = cmul((f32x2){z0.w, z1.w}, w[3]);
;                     XP[0] = (f32x4){a0.x, a0.y, a1.x, a1.y}; XP[1] = (f32x4){a2.x, a2.y, a3.x, a3.y}; } }
.LBB0_827:
	s_waitcnt vmcnt(2)
	v_ashrrev_i32_e32 v72, 4, v176
	v_lshlrev_b32_e32 v72, 3, v72
	v_and_b32_e32 v72, 0xffffffe0, v72
	v_lshlrev_b32_e32 v73, 3, v176
	v_add3_u32 v72, 0, v72, v73
	ds_write_b128 v72, v[80:83]
	ds_write_b128 v72, v[84:87] offset:16
	v_mov_b32_e32 v72, v140
	s_and_b64 vcc, exec, s[14:15]
	v_lshlrev_b32_e32 v82, 2, v72
	v_add_u32_e32 v176, 0x3800, v82
	s_cbranch_vccnz .LBB0_841
	s_waitcnt vmcnt(1)
	v_mov_b32_dpp v78, v71 wave_shr:1 row_mask:0xf bank_mask:0xf
	v_mov_b32_dpp v77, v68 wave_shl:1 row_mask:0xf bank_mask:0xf
	s_waitcnt vmcnt(0)
	v_mov_b32_dpp v74, v67 wave_shr:1 row_mask:0xf bank_mask:0xf
	v_mov_b32_dpp v73, v64 wave_shl:1 row_mask:0xf bank_mask:0xf
	s_and_saveexec_b64 s[14:15], s[8:9]
	s_cbranch_execz .LBB0_834
	v_cmp_lt_i32_e32 vcc, 0, v176
	s_waitcnt lgkmcnt(1)
	v_mov_b32_e32 v74, 0
	v_mov_b32_e32 v78, 0
	s_and_saveexec_b64 s[36:37], vcc
	s_cbranch_execz .LBB0_831
	v_lshl_add_u64 v[78:79], v[176:177], 2, s[20:21]
	global_load_dword v78, v[78:79], off offset:-4
